# FF1 sample-tile epilogue rewritten: 8 rss loads up front, per-row sw loads in a 3-buffer ring, batched rstd (was 16 serialized round trips)
# speedup vs baseline: 1.0014x; 1.0014x over previous
.LBB0_1318:
	v_readlane_b32 s52, v243, 56
	s_add_u32 s54, s36, 0x62d8000
	s_addc_u32 s55, s37, 0
	s_add_u32 s56, s36, 0x7670000
	s_addc_u32 s57, s37, 0
	s_mov_b32 s58, 0x2000
	s_mov_b32 s59, 0
	s_lshl_b32 s53, s52, 13
	s_lshl_b32 s52, s52, 9
	s_addk_i32 s52, 0x2000
	v_add_u32_e32 v182, s16, v151
	v_lshlrev_b32_e32 v172, 6, v182
	v_lshl_add_u32 v172, v150, 4, v172
	v_mov_b32_e32 v173, 0
	v_lshl_add_u64 v[172:173], s[54:55], 0, v[172:173]
	global_load_dwordx4 v[198:201], v[172:173], off
	global_load_dwordx4 v[202:205], v[172:173], off offset:1024
	global_load_dwordx4 v[206:209], v[172:173], off offset:2048
	global_load_dwordx4 v[210:213], v[172:173], off offset:3072
	v_lshl_add_u64 v[172:173], v[172:173], 0, s[58:59]
	global_load_dwordx4 v[224:227], v[172:173], off
	global_load_dwordx4 v[228:231], v[172:173], off offset:1024
	global_load_dwordx4 v[232:235], v[172:173], off offset:2048
	global_load_dwordx4 v[236:239], v[172:173], off offset:3072
	v_lshlrev_b32_e32 v183, 2, v144
	v_lshlrev_b32_e32 v171, 1, v144
	v_lshl_add_u32 v197, v182, 13, v171
	v_xor_b32_e32 v194, 16, v221
	v_lshlrev_b32_e32 v194, 2, v194
	v_xor_b32_e32 v196, 32, v221
	v_lshlrev_b32_e32 v196, 2, v196
	v_cmp_gt_i32_e32 vcc, s33, v182
	v_add_u32_e32 v167, s52, v182
	v_add_u32_e32 v168, s53, v182
	v_cndmask_b32_e32 v167, v167, v168, vcc
	v_cmp_gt_i32_e32 vcc, s90, v167
	v_add_u32_e32 v168, 0xffffc000, v167
	v_lshrrev_b32_e32 v168, 3, v168
	v_ashrrev_i32_e32 v169, 11, v167
	v_add_u32_e32 v168, 8, v168
	v_cndmask_b32_e32 v167, v168, v169, vcc
	v_lshl_add_u32 v171, v167, 14, v183
	global_load_dwordx4 v[104:107], v171, s[6:7]
	global_load_dwordx4 v[108:111], v171, s[6:7] offset:16
	global_load_dwordx4 v[124:127], v171, s[6:7] offset:512
	global_load_dwordx4 v[120:123], v171, s[6:7] offset:528
	s_waitcnt vmcnt(4)
	v_add_f32_e32 v174, v198, v199
	v_add_f32_e32 v186, v200, v201
	v_add_f32_e32 v175, v202, v203
	v_add_f32_e32 v187, v204, v205
	v_add_f32_e32 v176, v206, v207
	v_add_f32_e32 v188, v208, v209
	v_add_f32_e32 v177, v210, v211
	v_add_f32_e32 v189, v212, v213
	v_add_f32_e32 v178, v224, v225
	v_add_f32_e32 v190, v226, v227
	v_add_f32_e32 v179, v228, v229
	v_add_f32_e32 v191, v230, v231
	v_add_f32_e32 v180, v232, v233
	v_add_f32_e32 v192, v234, v235
	v_add_f32_e32 v181, v236, v237
	v_add_f32_e32 v193, v238, v239
	v_add_f32_e32 v174, v174, v186
	v_add_f32_e32 v175, v175, v187
	v_add_f32_e32 v176, v176, v188
	v_add_f32_e32 v177, v177, v189
	v_add_f32_e32 v178, v178, v190
	v_add_f32_e32 v179, v179, v191
	v_add_f32_e32 v180, v180, v192
	v_add_f32_e32 v181, v181, v193
	ds_bpermute_b32 v186, v194, v174
	ds_bpermute_b32 v187, v194, v175
	ds_bpermute_b32 v188, v194, v176
	ds_bpermute_b32 v189, v194, v177
	ds_bpermute_b32 v190, v194, v178
	ds_bpermute_b32 v191, v194, v179
	ds_bpermute_b32 v192, v194, v180
	ds_bpermute_b32 v193, v194, v181
	v_or_b32_e32 v170, 16, v182
	v_cmp_gt_i32_e32 vcc, s33, v170
	v_add_u32_e32 v167, s52, v170
	v_add_u32_e32 v168, s53, v170
	v_cndmask_b32_e32 v167, v167, v168, vcc
	v_cmp_gt_i32_e32 vcc, s90, v167
	v_add_u32_e32 v168, 0xffffc000, v167
	v_lshrrev_b32_e32 v168, 3, v168
	v_ashrrev_i32_e32 v169, 11, v167
	v_add_u32_e32 v168, 8, v168
	v_cndmask_b32_e32 v167, v168, v169, vcc
	v_lshl_add_u32 v171, v167, 14, v183
	global_load_dwordx4 v[198:201], v171, s[6:7]
	global_load_dwordx4 v[202:205], v171, s[6:7] offset:16
	global_load_dwordx4 v[206:209], v171, s[6:7] offset:512
	global_load_dwordx4 v[210:213], v171, s[6:7] offset:528
	s_waitcnt lgkmcnt(0)
	v_add_f32_e32 v174, v174, v186
	v_add_f32_e32 v175, v175, v187
	v_add_f32_e32 v176, v176, v188
	v_add_f32_e32 v177, v177, v189
	v_add_f32_e32 v178, v178, v190
	v_add_f32_e32 v179, v179, v191
	v_add_f32_e32 v180, v180, v192
	v_add_f32_e32 v181, v181, v193
	ds_bpermute_b32 v186, v196, v174
	ds_bpermute_b32 v187, v196, v175
	ds_bpermute_b32 v188, v196, v176
	ds_bpermute_b32 v189, v196, v177
	ds_bpermute_b32 v190, v196, v178
	ds_bpermute_b32 v191, v196, v179
	ds_bpermute_b32 v192, v196, v180
	ds_bpermute_b32 v193, v196, v181
	v_or_b32_e32 v170, 32, v182
	v_cmp_gt_i32_e32 vcc, s33, v170
	v_add_u32_e32 v167, s52, v170
	v_add_u32_e32 v168, s53, v170
	v_cndmask_b32_e32 v167, v167, v168, vcc
	v_cmp_gt_i32_e32 vcc, s90, v167
	v_add_u32_e32 v168, 0xffffc000, v167
	v_lshrrev_b32_e32 v168, 3, v168
	v_ashrrev_i32_e32 v169, 11, v167
	v_add_u32_e32 v168, 8, v168
	v_cndmask_b32_e32 v167, v168, v169, vcc
	v_lshl_add_u32 v171, v167, 14, v183
	global_load_dwordx4 v[224:227], v171, s[6:7]
	global_load_dwordx4 v[228:231], v171, s[6:7] offset:16
	global_load_dwordx4 v[232:235], v171, s[6:7] offset:512
	global_load_dwordx4 v[236:239], v171, s[6:7] offset:528
	s_waitcnt lgkmcnt(0)
	v_add_f32_e32 v174, v174, v186
	v_add_f32_e32 v175, v175, v187
	v_add_f32_e32 v176, v176, v188
	v_add_f32_e32 v177, v177, v189
	v_add_f32_e32 v178, v178, v190
	v_add_f32_e32 v179, v179, v191
	v_add_f32_e32 v180, v180, v192
	v_add_f32_e32 v181, v181, v193
	v_fmamk_f32 v174, v174, 0x3a800000, v216
	v_fmamk_f32 v175, v175, 0x3a800000, v216
	v_fmamk_f32 v176, v176, 0x3a800000, v216
	v_fmamk_f32 v177, v177, 0x3a800000, v216
	v_fmamk_f32 v178, v178, 0x3a800000, v216
	v_fmamk_f32 v179, v179, 0x3a800000, v216
	v_fmamk_f32 v180, v180, 0x3a800000, v216
	v_fmamk_f32 v181, v181, 0x3a800000, v216
	v_rsq_f32_e32 v174, v174
	v_rsq_f32_e32 v175, v175
	v_rsq_f32_e32 v176, v176
	v_rsq_f32_e32 v177, v177
	v_rsq_f32_e32 v178, v178
	v_rsq_f32_e32 v179, v179
	v_rsq_f32_e32 v180, v180
	v_rsq_f32_e32 v181, v181
	s_nop 0
	s_waitcnt vmcnt(8)
	v_pk_fma_f32 v[142:143], v[142:143], v[174:175], v[106:107] op_sel_hi:[1,0,1]
	v_pk_fma_f32 v[140:141], v[140:141], v[174:175], v[104:105] op_sel_hi:[1,0,1]
	v_pk_fma_f32 v[138:139], v[138:139], v[174:175], v[110:111] op_sel_hi:[1,0,1]
	v_pk_fma_f32 v[136:137], v[136:137], v[174:175], v[108:109] op_sel_hi:[1,0,1]
	v_pk_fma_f32 v[134:135], v[134:135], v[174:175], v[126:127] op_sel_hi:[1,0,1]
	v_pk_fma_f32 v[132:133], v[132:133], v[174:175], v[124:125] op_sel_hi:[1,0,1]
	v_pk_fma_f32 v[130:131], v[130:131], v[174:175], v[122:123] op_sel_hi:[1,0,1]
	v_pk_fma_f32 v[128:129], v[128:129], v[174:175], v[120:121] op_sel_hi:[1,0,1]
	v_max_f32_e32 v140, 0, v140
	v_max_f32_e32 v141, 0, v141
	v_max_f32_e32 v142, 0, v142
	v_max_f32_e32 v143, 0, v143
	v_max_f32_e32 v136, 0, v136
	v_max_f32_e32 v137, 0, v137
	v_max_f32_e32 v138, 0, v138
	v_max_f32_e32 v139, 0, v139
	v_mul_f32_e32 v140, v140, v140
	v_mul_f32_e32 v141, v141, v141
	v_mul_f32_e32 v142, v142, v142
	v_mul_f32_e32 v143, v143, v143
	v_mul_f32_e32 v136, v136, v136
	v_mul_f32_e32 v137, v137, v137
	v_mul_f32_e32 v138, v138, v138
	v_mul_f32_e32 v139, v139, v139
	v_cvt_pk_bf16_f32 v140, v140, v141
	v_cvt_pk_bf16_f32 v141, v142, v143
	v_cvt_pk_bf16_f32 v142, v136, v137
	v_cvt_pk_bf16_f32 v143, v138, v139
	global_store_dwordx4 v197, v[140:143], s[56:57] sc0 sc1
	v_max_f32_e32 v132, 0, v132
	v_max_f32_e32 v133, 0, v133
	v_max_f32_e32 v134, 0, v134
	v_max_f32_e32 v135, 0, v135
	v_max_f32_e32 v128, 0, v128
	v_max_f32_e32 v129, 0, v129
	v_max_f32_e32 v130, 0, v130
	v_max_f32_e32 v131, 0, v131
	v_mul_f32_e32 v132, v132, v132
	v_mul_f32_e32 v133, v133, v133
	v_mul_f32_e32 v134, v134, v134
	v_mul_f32_e32 v135, v135, v135
	v_mul_f32_e32 v128, v128, v128
	v_mul_f32_e32 v129, v129, v129
	v_mul_f32_e32 v130, v130, v130
	v_mul_f32_e32 v131, v131, v131
	v_cvt_pk_bf16_f32 v132, v132, v133
	v_cvt_pk_bf16_f32 v133, v134, v135
	v_cvt_pk_bf16_f32 v134, v128, v129
	v_cvt_pk_bf16_f32 v135, v130, v131
	global_store_dwordx4 v197, v[132:135], s[56:57] offset:256 sc0 sc1
	v_add_u32_e32 v240, 0x20000, v197
	v_or_b32_e32 v170, 48, v182
	v_cmp_gt_i32_e32 vcc, s33, v170
	v_add_u32_e32 v167, s52, v170
	v_add_u32_e32 v168, s53, v170
	v_cndmask_b32_e32 v167, v167, v168, vcc
	v_cmp_gt_i32_e32 vcc, s90, v167
	v_add_u32_e32 v168, 0xffffc000, v167
	v_lshrrev_b32_e32 v168, 3, v168
	v_ashrrev_i32_e32 v169, 11, v167
	v_add_u32_e32 v168, 8, v168
	v_cndmask_b32_e32 v167, v168, v169, vcc
	v_lshl_add_u32 v171, v167, 14, v183
	global_load_dwordx4 v[104:107], v171, s[6:7]
	global_load_dwordx4 v[108:111], v171, s[6:7] offset:16
	global_load_dwordx4 v[124:127], v171, s[6:7] offset:512
	global_load_dwordx4 v[120:123], v171, s[6:7] offset:528
	s_waitcnt vmcnt(10)
	v_pk_fma_f32 v[118:119], v[118:119], v[174:175], v[200:201] op_sel:[0,1,0] op_sel_hi:[1,1,1]
	v_pk_fma_f32 v[116:117], v[116:117], v[174:175], v[198:199] op_sel:[0,1,0] op_sel_hi:[1,1,1]
	v_pk_fma_f32 v[114:115], v[114:115], v[174:175], v[204:205] op_sel:[0,1,0] op_sel_hi:[1,1,1]
	v_pk_fma_f32 v[112:113], v[112:113], v[174:175], v[202:203] op_sel:[0,1,0] op_sel_hi:[1,1,1]
	v_pk_fma_f32 v[102:103], v[102:103], v[174:175], v[208:209] op_sel:[0,1,0] op_sel_hi:[1,1,1]
	v_pk_fma_f32 v[100:101], v[100:101], v[174:175], v[206:207] op_sel:[0,1,0] op_sel_hi:[1,1,1]
	v_pk_fma_f32 v[98:99], v[98:99], v[174:175], v[212:213] op_sel:[0,1,0] op_sel_hi:[1,1,1]
	v_pk_fma_f32 v[96:97], v[96:97], v[174:175], v[210:211] op_sel:[0,1,0] op_sel_hi:[1,1,1]
	v_max_f32_e32 v116, 0, v116
	v_max_f32_e32 v117, 0, v117
	v_max_f32_e32 v118, 0, v118
	v_max_f32_e32 v119, 0, v119
	v_max_f32_e32 v112, 0, v112
	v_max_f32_e32 v113, 0, v113
	v_max_f32_e32 v114, 0, v114
	v_max_f32_e32 v115, 0, v115
	v_mul_f32_e32 v116, v116, v116
	v_mul_f32_e32 v117, v117, v117
	v_mul_f32_e32 v118, v118, v118
	v_mul_f32_e32 v119, v119, v119
	v_mul_f32_e32 v112, v112, v112
	v_mul_f32_e32 v113, v113, v113
	v_mul_f32_e32 v114, v114, v114
	v_mul_f32_e32 v115, v115, v115
	v_cvt_pk_bf16_f32 v116, v116, v117
	v_cvt_pk_bf16_f32 v117, v118, v119
	v_cvt_pk_bf16_f32 v118, v112, v113
	v_cvt_pk_bf16_f32 v119, v114, v115
	global_store_dwordx4 v240, v[116:119], s[56:57] sc0 sc1
	v_max_f32_e32 v100, 0, v100
	v_max_f32_e32 v101, 0, v101
	v_max_f32_e32 v102, 0, v102
	v_max_f32_e32 v103, 0, v103
	v_max_f32_e32 v96, 0, v96
	v_max_f32_e32 v97, 0, v97
	v_max_f32_e32 v98, 0, v98
	v_max_f32_e32 v99, 0, v99
	v_mul_f32_e32 v100, v100, v100
	v_mul_f32_e32 v101, v101, v101
	v_mul_f32_e32 v102, v102, v102
	v_mul_f32_e32 v103, v103, v103
	v_mul_f32_e32 v96, v96, v96
	v_mul_f32_e32 v97, v97, v97
	v_mul_f32_e32 v98, v98, v98
	v_mul_f32_e32 v99, v99, v99
	v_cvt_pk_bf16_f32 v100, v100, v101
	v_cvt_pk_bf16_f32 v101, v102, v103
	v_cvt_pk_bf16_f32 v102, v96, v97
	v_cvt_pk_bf16_f32 v103, v98, v99
	global_store_dwordx4 v240, v[100:103], s[56:57] offset:256 sc0 sc1
	v_add_u32_e32 v197, 0x20000, v240
	v_add_u32_e32 v170, 0x80, v182
	v_cmp_gt_i32_e32 vcc, s33, v170
	v_add_u32_e32 v167, s52, v170
	v_add_u32_e32 v168, s53, v170
	v_cndmask_b32_e32 v167, v167, v168, vcc
	v_cmp_gt_i32_e32 vcc, s90, v167
	v_add_u32_e32 v168, 0xffffc000, v167
	v_lshrrev_b32_e32 v168, 3, v168
	v_ashrrev_i32_e32 v169, 11, v167
	v_add_u32_e32 v168, 8, v168
	v_cndmask_b32_e32 v167, v168, v169, vcc
	v_lshl_add_u32 v171, v167, 14, v183
	global_load_dwordx4 v[198:201], v171, s[6:7]
	global_load_dwordx4 v[202:205], v171, s[6:7] offset:16
	global_load_dwordx4 v[206:209], v171, s[6:7] offset:512
	global_load_dwordx4 v[210:213], v171, s[6:7] offset:528
	s_waitcnt vmcnt(12)
	v_pk_fma_f32 v[94:95], v[94:95], v[176:177], v[226:227] op_sel_hi:[1,0,1]
	v_pk_fma_f32 v[92:93], v[92:93], v[176:177], v[224:225] op_sel_hi:[1,0,1]
	v_pk_fma_f32 v[90:91], v[90:91], v[176:177], v[230:231] op_sel_hi:[1,0,1]
	v_pk_fma_f32 v[88:89], v[88:89], v[176:177], v[228:229] op_sel_hi:[1,0,1]
	v_pk_fma_f32 v[86:87], v[86:87], v[176:177], v[234:235] op_sel_hi:[1,0,1]
	v_pk_fma_f32 v[84:85], v[84:85], v[176:177], v[232:233] op_sel_hi:[1,0,1]
	v_pk_fma_f32 v[82:83], v[82:83], v[176:177], v[238:239] op_sel_hi:[1,0,1]
	v_pk_fma_f32 v[80:81], v[80:81], v[176:177], v[236:237] op_sel_hi:[1,0,1]
	v_max_f32_e32 v92, 0, v92
	v_max_f32_e32 v93, 0, v93
	v_max_f32_e32 v94, 0, v94
	v_max_f32_e32 v95, 0, v95
	v_max_f32_e32 v88, 0, v88
	v_max_f32_e32 v89, 0, v89
	v_max_f32_e32 v90, 0, v90
	v_max_f32_e32 v91, 0, v91
	v_mul_f32_e32 v92, v92, v92
	v_mul_f32_e32 v93, v93, v93
	v_mul_f32_e32 v94, v94, v94
	v_mul_f32_e32 v95, v95, v95
	v_mul_f32_e32 v88, v88, v88
	v_mul_f32_e32 v89, v89, v89
	v_mul_f32_e32 v90, v90, v90
	v_mul_f32_e32 v91, v91, v91
	v_cvt_pk_bf16_f32 v92, v92, v93
	v_cvt_pk_bf16_f32 v93, v94, v95
	v_cvt_pk_bf16_f32 v94, v88, v89
	v_cvt_pk_bf16_f32 v95, v90, v91
	global_store_dwordx4 v197, v[92:95], s[56:57] sc0 sc1
	v_max_f32_e32 v84, 0, v84
	v_max_f32_e32 v85, 0, v85
	v_max_f32_e32 v86, 0, v86
	v_max_f32_e32 v87, 0, v87
	v_max_f32_e32 v80, 0, v80
	v_max_f32_e32 v81, 0, v81
	v_max_f32_e32 v82, 0, v82
	v_max_f32_e32 v83, 0, v83
	v_mul_f32_e32 v84, v84, v84
	v_mul_f32_e32 v85, v85, v85
	v_mul_f32_e32 v86, v86, v86
	v_mul_f32_e32 v87, v87, v87
	v_mul_f32_e32 v80, v80, v80
	v_mul_f32_e32 v81, v81, v81
	v_mul_f32_e32 v82, v82, v82
	v_mul_f32_e32 v83, v83, v83
	v_cvt_pk_bf16_f32 v84, v84, v85
	v_cvt_pk_bf16_f32 v85, v86, v87
	v_cvt_pk_bf16_f32 v86, v80, v81
	v_cvt_pk_bf16_f32 v87, v82, v83
	global_store_dwordx4 v197, v[84:87], s[56:57] offset:256 sc0 sc1
	v_add_u32_e32 v240, 0x20000, v197
	v_add_u32_e32 v170, 0x90, v182
	v_cmp_gt_i32_e32 vcc, s33, v170
	v_add_u32_e32 v167, s52, v170
	v_add_u32_e32 v168, s53, v170
	v_cndmask_b32_e32 v167, v167, v168, vcc
	v_cmp_gt_i32_e32 vcc, s90, v167
	v_add_u32_e32 v168, 0xffffc000, v167
	v_lshrrev_b32_e32 v168, 3, v168
	v_ashrrev_i32_e32 v169, 11, v167
	v_add_u32_e32 v168, 8, v168
	v_cndmask_b32_e32 v167, v168, v169, vcc
	v_lshl_add_u32 v171, v167, 14, v183
	global_load_dwordx4 v[224:227], v171, s[6:7]
	global_load_dwordx4 v[228:231], v171, s[6:7] offset:16
	global_load_dwordx4 v[232:235], v171, s[6:7] offset:512
	global_load_dwordx4 v[236:239], v171, s[6:7] offset:528
	s_waitcnt vmcnt(12)
	v_pk_fma_f32 v[78:79], v[78:79], v[176:177], v[106:107] op_sel:[0,1,0] op_sel_hi:[1,1,1]
	v_pk_fma_f32 v[76:77], v[76:77], v[176:177], v[104:105] op_sel:[0,1,0] op_sel_hi:[1,1,1]
	v_pk_fma_f32 v[74:75], v[74:75], v[176:177], v[110:111] op_sel:[0,1,0] op_sel_hi:[1,1,1]
	v_pk_fma_f32 v[72:73], v[72:73], v[176:177], v[108:109] op_sel:[0,1,0] op_sel_hi:[1,1,1]
	v_pk_fma_f32 v[70:71], v[70:71], v[176:177], v[126:127] op_sel:[0,1,0] op_sel_hi:[1,1,1]
	v_pk_fma_f32 v[68:69], v[68:69], v[176:177], v[124:125] op_sel:[0,1,0] op_sel_hi:[1,1,1]
	v_pk_fma_f32 v[66:67], v[66:67], v[176:177], v[122:123] op_sel:[0,1,0] op_sel_hi:[1,1,1]
	v_pk_fma_f32 v[64:65], v[64:65], v[176:177], v[120:121] op_sel:[0,1,0] op_sel_hi:[1,1,1]
	v_max_f32_e32 v76, 0, v76
	v_max_f32_e32 v77, 0, v77
	v_max_f32_e32 v78, 0, v78
	v_max_f32_e32 v79, 0, v79
	v_max_f32_e32 v72, 0, v72
	v_max_f32_e32 v73, 0, v73
	v_max_f32_e32 v74, 0, v74
	v_max_f32_e32 v75, 0, v75
	v_mul_f32_e32 v76, v76, v76
	v_mul_f32_e32 v77, v77, v77
	v_mul_f32_e32 v78, v78, v78
	v_mul_f32_e32 v79, v79, v79
	v_mul_f32_e32 v72, v72, v72
	v_mul_f32_e32 v73, v73, v73
	v_mul_f32_e32 v74, v74, v74
	v_mul_f32_e32 v75, v75, v75
	v_cvt_pk_bf16_f32 v76, v76, v77
	v_cvt_pk_bf16_f32 v77, v78, v79
	v_cvt_pk_bf16_f32 v78, v72, v73
	v_cvt_pk_bf16_f32 v79, v74, v75
	global_store_dwordx4 v240, v[76:79], s[56:57] sc0 sc1
	v_max_f32_e32 v68, 0, v68
	v_max_f32_e32 v69, 0, v69
	v_max_f32_e32 v70, 0, v70
	v_max_f32_e32 v71, 0, v71
	v_max_f32_e32 v64, 0, v64
	v_max_f32_e32 v65, 0, v65
	v_max_f32_e32 v66, 0, v66
	v_max_f32_e32 v67, 0, v67
	v_mul_f32_e32 v68, v68, v68
	v_mul_f32_e32 v69, v69, v69
	v_mul_f32_e32 v70, v70, v70
	v_mul_f32_e32 v71, v71, v71
	v_mul_f32_e32 v64, v64, v64
	v_mul_f32_e32 v65, v65, v65
	v_mul_f32_e32 v66, v66, v66
	v_mul_f32_e32 v67, v67, v67
	v_cvt_pk_bf16_f32 v68, v68, v69
	v_cvt_pk_bf16_f32 v69, v70, v71
	v_cvt_pk_bf16_f32 v70, v64, v65
	v_cvt_pk_bf16_f32 v71, v66, v67
	global_store_dwordx4 v240, v[68:71], s[56:57] offset:256 sc0 sc1
	v_add_u32_e32 v197, 0xa0000, v240
	v_add_u32_e32 v170, 0xa0, v182
	v_cmp_gt_i32_e32 vcc, s33, v170
	v_add_u32_e32 v167, s52, v170
	v_add_u32_e32 v168, s53, v170
	v_cndmask_b32_e32 v167, v167, v168, vcc
	v_cmp_gt_i32_e32 vcc, s90, v167
	v_add_u32_e32 v168, 0xffffc000, v167
	v_lshrrev_b32_e32 v168, 3, v168
	v_ashrrev_i32_e32 v169, 11, v167
	v_add_u32_e32 v168, 8, v168
	v_cndmask_b32_e32 v167, v168, v169, vcc
	v_lshl_add_u32 v171, v167, 14, v183
	global_load_dwordx4 v[104:107], v171, s[6:7]
	global_load_dwordx4 v[108:111], v171, s[6:7] offset:16
	global_load_dwordx4 v[124:127], v171, s[6:7] offset:512
	global_load_dwordx4 v[120:123], v171, s[6:7] offset:528
	s_waitcnt vmcnt(12)
	v_pk_fma_f32 v[62:63], v[62:63], v[178:179], v[200:201] op_sel_hi:[1,0,1]
	v_pk_fma_f32 v[60:61], v[60:61], v[178:179], v[198:199] op_sel_hi:[1,0,1]
	v_pk_fma_f32 v[58:59], v[58:59], v[178:179], v[204:205] op_sel_hi:[1,0,1]
	v_pk_fma_f32 v[56:57], v[56:57], v[178:179], v[202:203] op_sel_hi:[1,0,1]
	v_pk_fma_f32 v[54:55], v[54:55], v[178:179], v[208:209] op_sel_hi:[1,0,1]
	v_pk_fma_f32 v[52:53], v[52:53], v[178:179], v[206:207] op_sel_hi:[1,0,1]
	v_pk_fma_f32 v[50:51], v[50:51], v[178:179], v[212:213] op_sel_hi:[1,0,1]
	v_pk_fma_f32 v[48:49], v[48:49], v[178:179], v[210:211] op_sel_hi:[1,0,1]
	v_max_f32_e32 v60, 0, v60
	v_max_f32_e32 v61, 0, v61
	v_max_f32_e32 v62, 0, v62
	v_max_f32_e32 v63, 0, v63
	v_max_f32_e32 v56, 0, v56
	v_max_f32_e32 v57, 0, v57
	v_max_f32_e32 v58, 0, v58
	v_max_f32_e32 v59, 0, v59
	v_mul_f32_e32 v60, v60, v60
	v_mul_f32_e32 v61, v61, v61
	v_mul_f32_e32 v62, v62, v62
	v_mul_f32_e32 v63, v63, v63
	v_mul_f32_e32 v56, v56, v56
	v_mul_f32_e32 v57, v57, v57
	v_mul_f32_e32 v58, v58, v58
	v_mul_f32_e32 v59, v59, v59
	v_cvt_pk_bf16_f32 v60, v60, v61
	v_cvt_pk_bf16_f32 v61, v62, v63
	v_cvt_pk_bf16_f32 v62, v56, v57
	v_cvt_pk_bf16_f32 v63, v58, v59
	global_store_dwordx4 v197, v[60:63], s[56:57] sc0 sc1
	v_max_f32_e32 v52, 0, v52
	v_max_f32_e32 v53, 0, v53
	v_max_f32_e32 v54, 0, v54
	v_max_f32_e32 v55, 0, v55
	v_max_f32_e32 v48, 0, v48
	v_max_f32_e32 v49, 0, v49
	v_max_f32_e32 v50, 0, v50
	v_max_f32_e32 v51, 0, v51
	v_mul_f32_e32 v52, v52, v52
	v_mul_f32_e32 v53, v53, v53
	v_mul_f32_e32 v54, v54, v54
	v_mul_f32_e32 v55, v55, v55
	v_mul_f32_e32 v48, v48, v48
	v_mul_f32_e32 v49, v49, v49
	v_mul_f32_e32 v50, v50, v50
	v_mul_f32_e32 v51, v51, v51
	v_cvt_pk_bf16_f32 v52, v52, v53
	v_cvt_pk_bf16_f32 v53, v54, v55
	v_cvt_pk_bf16_f32 v54, v48, v49
	v_cvt_pk_bf16_f32 v55, v50, v51
	global_store_dwordx4 v197, v[52:55], s[56:57] offset:256 sc0 sc1
	v_add_u32_e32 v240, 0x20000, v197
	v_add_u32_e32 v170, 0xb0, v182
	v_cmp_gt_i32_e32 vcc, s33, v170
	v_add_u32_e32 v167, s52, v170
	v_add_u32_e32 v168, s53, v170
	v_cndmask_b32_e32 v167, v167, v168, vcc
	v_cmp_gt_i32_e32 vcc, s90, v167
	v_add_u32_e32 v168, 0xffffc000, v167
	v_lshrrev_b32_e32 v168, 3, v168
	v_ashrrev_i32_e32 v169, 11, v167
	v_add_u32_e32 v168, 8, v168
	v_cndmask_b32_e32 v167, v168, v169, vcc
	v_lshl_add_u32 v171, v167, 14, v183
	global_load_dwordx4 v[198:201], v171, s[6:7]
	global_load_dwordx4 v[202:205], v171, s[6:7] offset:16
	global_load_dwordx4 v[206:209], v171, s[6:7] offset:512
	global_load_dwordx4 v[210:213], v171, s[6:7] offset:528
	s_waitcnt vmcnt(12)
	v_pk_fma_f32 v[46:47], v[46:47], v[178:179], v[226:227] op_sel:[0,1,0] op_sel_hi:[1,1,1]
	v_pk_fma_f32 v[44:45], v[44:45], v[178:179], v[224:225] op_sel:[0,1,0] op_sel_hi:[1,1,1]
	v_pk_fma_f32 v[42:43], v[42:43], v[178:179], v[230:231] op_sel:[0,1,0] op_sel_hi:[1,1,1]
	v_pk_fma_f32 v[40:41], v[40:41], v[178:179], v[228:229] op_sel:[0,1,0] op_sel_hi:[1,1,1]
	v_pk_fma_f32 v[38:39], v[38:39], v[178:179], v[234:235] op_sel:[0,1,0] op_sel_hi:[1,1,1]
	v_pk_fma_f32 v[36:37], v[36:37], v[178:179], v[232:233] op_sel:[0,1,0] op_sel_hi:[1,1,1]
	v_pk_fma_f32 v[34:35], v[34:35], v[178:179], v[238:239] op_sel:[0,1,0] op_sel_hi:[1,1,1]
	v_pk_fma_f32 v[32:33], v[32:33], v[178:179], v[236:237] op_sel:[0,1,0] op_sel_hi:[1,1,1]
	v_max_f32_e32 v44, 0, v44
	v_max_f32_e32 v45, 0, v45
	v_max_f32_e32 v46, 0, v46
	v_max_f32_e32 v47, 0, v47
	v_max_f32_e32 v40, 0, v40
	v_max_f32_e32 v41, 0, v41
	v_max_f32_e32 v42, 0, v42
	v_max_f32_e32 v43, 0, v43
	v_mul_f32_e32 v44, v44, v44
	v_mul_f32_e32 v45, v45, v45
	v_mul_f32_e32 v46, v46, v46
	v_mul_f32_e32 v47, v47, v47
	v_mul_f32_e32 v40, v40, v40
	v_mul_f32_e32 v41, v41, v41
	v_mul_f32_e32 v42, v42, v42
	v_mul_f32_e32 v43, v43, v43
	v_cvt_pk_bf16_f32 v44, v44, v45
	v_cvt_pk_bf16_f32 v45, v46, v47
	v_cvt_pk_bf16_f32 v46, v40, v41
	v_cvt_pk_bf16_f32 v47, v42, v43
	global_store_dwordx4 v240, v[44:47], s[56:57] sc0 sc1
	v_max_f32_e32 v36, 0, v36
	v_max_f32_e32 v37, 0, v37
	v_max_f32_e32 v38, 0, v38
	v_max_f32_e32 v39, 0, v39
	v_max_f32_e32 v32, 0, v32
	v_max_f32_e32 v33, 0, v33
	v_max_f32_e32 v34, 0, v34
	v_max_f32_e32 v35, 0, v35
	v_mul_f32_e32 v36, v36, v36
	v_mul_f32_e32 v37, v37, v37
	v_mul_f32_e32 v38, v38, v38
	v_mul_f32_e32 v39, v39, v39
	v_mul_f32_e32 v32, v32, v32
	v_mul_f32_e32 v33, v33, v33
	v_mul_f32_e32 v34, v34, v34
	v_mul_f32_e32 v35, v35, v35
	v_cvt_pk_bf16_f32 v36, v36, v37
	v_cvt_pk_bf16_f32 v37, v38, v39
	v_cvt_pk_bf16_f32 v38, v32, v33
	v_cvt_pk_bf16_f32 v39, v34, v35
	global_store_dwordx4 v240, v[36:39], s[56:57] offset:256 sc0 sc1
	v_add_u32_e32 v197, 0x20000, v240
	s_waitcnt vmcnt(8)
	v_pk_fma_f32 v[30:31], v[30:31], v[180:181], v[106:107] op_sel_hi:[1,0,1]
	v_pk_fma_f32 v[28:29], v[28:29], v[180:181], v[104:105] op_sel_hi:[1,0,1]
	v_pk_fma_f32 v[26:27], v[26:27], v[180:181], v[110:111] op_sel_hi:[1,0,1]
	v_pk_fma_f32 v[24:25], v[24:25], v[180:181], v[108:109] op_sel_hi:[1,0,1]
	v_pk_fma_f32 v[22:23], v[22:23], v[180:181], v[126:127] op_sel_hi:[1,0,1]
	v_pk_fma_f32 v[20:21], v[20:21], v[180:181], v[124:125] op_sel_hi:[1,0,1]
	v_pk_fma_f32 v[18:19], v[18:19], v[180:181], v[122:123] op_sel_hi:[1,0,1]
	v_pk_fma_f32 v[16:17], v[16:17], v[180:181], v[120:121] op_sel_hi:[1,0,1]
	v_max_f32_e32 v28, 0, v28
	v_max_f32_e32 v29, 0, v29
	v_max_f32_e32 v30, 0, v30
	v_max_f32_e32 v31, 0, v31
	v_max_f32_e32 v24, 0, v24
	v_max_f32_e32 v25, 0, v25
	v_max_f32_e32 v26, 0, v26
	v_max_f32_e32 v27, 0, v27
	v_mul_f32_e32 v28, v28, v28
	v_mul_f32_e32 v29, v29, v29
	v_mul_f32_e32 v30, v30, v30
	v_mul_f32_e32 v31, v31, v31
	v_mul_f32_e32 v24, v24, v24
	v_mul_f32_e32 v25, v25, v25
	v_mul_f32_e32 v26, v26, v26
	v_mul_f32_e32 v27, v27, v27
	v_cvt_pk_bf16_f32 v28, v28, v29
	v_cvt_pk_bf16_f32 v29, v30, v31
	v_cvt_pk_bf16_f32 v30, v24, v25
	v_cvt_pk_bf16_f32 v31, v26, v27
	global_store_dwordx4 v197, v[28:31], s[56:57] sc0 sc1
	v_max_f32_e32 v20, 0, v20
	v_max_f32_e32 v21, 0, v21
	v_max_f32_e32 v22, 0, v22
	v_max_f32_e32 v23, 0, v23
	v_max_f32_e32 v16, 0, v16
	v_max_f32_e32 v17, 0, v17
	v_max_f32_e32 v18, 0, v18
	v_max_f32_e32 v19, 0, v19
	v_mul_f32_e32 v20, v20, v20
	v_mul_f32_e32 v21, v21, v21
	v_mul_f32_e32 v22, v22, v22
	v_mul_f32_e32 v23, v23, v23
	v_mul_f32_e32 v16, v16, v16
	v_mul_f32_e32 v17, v17, v17
	v_mul_f32_e32 v18, v18, v18
	v_mul_f32_e32 v19, v19, v19
	v_cvt_pk_bf16_f32 v20, v20, v21
	v_cvt_pk_bf16_f32 v21, v22, v23
	v_cvt_pk_bf16_f32 v22, v16, v17
	v_cvt_pk_bf16_f32 v23, v18, v19
	global_store_dwordx4 v197, v[20:23], s[56:57] offset:256 sc0 sc1
	v_add_u32_e32 v240, 0x20000, v197
	s_waitcnt vmcnt(4)
	v_pk_fma_f32 v[14:15], v[14:15], v[180:181], v[200:201] op_sel:[0,1,0] op_sel_hi:[1,1,1]
	v_pk_fma_f32 v[12:13], v[12:13], v[180:181], v[198:199] op_sel:[0,1,0] op_sel_hi:[1,1,1]
	v_pk_fma_f32 v[10:11], v[10:11], v[180:181], v[204:205] op_sel:[0,1,0] op_sel_hi:[1,1,1]
	v_pk_fma_f32 v[8:9], v[8:9], v[180:181], v[202:203] op_sel:[0,1,0] op_sel_hi:[1,1,1]
	v_pk_fma_f32 v[6:7], v[6:7], v[180:181], v[208:209] op_sel:[0,1,0] op_sel_hi:[1,1,1]
	v_pk_fma_f32 v[4:5], v[4:5], v[180:181], v[206:207] op_sel:[0,1,0] op_sel_hi:[1,1,1]
	v_pk_fma_f32 v[2:3], v[2:3], v[180:181], v[212:213] op_sel:[0,1,0] op_sel_hi:[1,1,1]
	v_pk_fma_f32 v[0:1], v[0:1], v[180:181], v[210:211] op_sel:[0,1,0] op_sel_hi:[1,1,1]
	v_max_f32_e32 v12, 0, v12
	v_max_f32_e32 v13, 0, v13
	v_max_f32_e32 v14, 0, v14
	v_max_f32_e32 v15, 0, v15
	v_max_f32_e32 v8, 0, v8
	v_max_f32_e32 v9, 0, v9
	v_max_f32_e32 v10, 0, v10
	v_max_f32_e32 v11, 0, v11
	v_mul_f32_e32 v12, v12, v12
	v_mul_f32_e32 v13, v13, v13
	v_mul_f32_e32 v14, v14, v14
	v_mul_f32_e32 v15, v15, v15
	v_mul_f32_e32 v8, v8, v8
	v_mul_f32_e32 v9, v9, v9
	v_mul_f32_e32 v10, v10, v10
	v_mul_f32_e32 v11, v11, v11
	v_cvt_pk_bf16_f32 v12, v12, v13
	v_cvt_pk_bf16_f32 v13, v14, v15
	v_cvt_pk_bf16_f32 v14, v8, v9
	v_cvt_pk_bf16_f32 v15, v10, v11
	global_store_dwordx4 v240, v[12:15], s[56:57] sc0 sc1
	v_max_f32_e32 v4, 0, v4
	v_max_f32_e32 v5, 0, v5
	v_max_f32_e32 v6, 0, v6
	v_max_f32_e32 v7, 0, v7
	v_max_f32_e32 v0, 0, v0
	v_max_f32_e32 v1, 0, v1
	v_max_f32_e32 v2, 0, v2
	v_max_f32_e32 v3, 0, v3
	v_mul_f32_e32 v4, v4, v4
	v_mul_f32_e32 v5, v5, v5
	v_mul_f32_e32 v6, v6, v6
	v_mul_f32_e32 v7, v7, v7
	v_mul_f32_e32 v0, v0, v0
	v_mul_f32_e32 v1, v1, v1
	v_mul_f32_e32 v2, v2, v2
	v_mul_f32_e32 v3, v3, v3
	v_cvt_pk_bf16_f32 v4, v4, v5
	v_cvt_pk_bf16_f32 v5, v6, v7
	v_cvt_pk_bf16_f32 v6, v0, v1
	v_cvt_pk_bf16_f32 v7, v2, v3
	global_store_dwordx4 v240, v[4:7], s[56:57] offset:256 sc0 sc1
	s_or_b32 s3, s1, s0
	s_lshl_b32 s0, s22, 6
	s_ashr_i32 s1, s0, 31
	s_lshl_b64 s[0:1], s[0:1], 2
	s_add_u32 s0, s36, s0
	s_addc_u32 s1, s37, s1
	v_readlane_b32 s6, v243, 9
	v_readlane_b32 s7, v243, 10
	s_add_u32 s0, s0, s6
	s_addc_u32 s1, s1, s7
	s_add_u32 s6, s0, 0x11086000
	s_waitcnt vmcnt(0)
	s_addc_u32 s7, s1, 0
	s_cmp_lg_u32 s3, 0
	s_barrier
	s_cbranch_scc1 .LBB0_1373
	s_waitcnt vmcnt(0)
	s_waitcnt vmcnt(0)
	v_or_b32_e32 v0, v150, v145
	v_cmp_eq_u32_e32 vcc, 0, v0
	s_and_saveexec_b64 s[8:9], vcc
	s_cbranch_execz .LBB0_1372
	s_mov_b64 s[10:11], exec
	v_mbcnt_lo_u32_b32 v0, s10, 0
	v_mbcnt_hi_u32_b32 v0, s11, v0
	v_cmp_eq_u32_e32 vcc, 0, v0
	s_and_b64 s[0:1], exec, vcc
	s_mov_b64 exec, s[0:1]
	s_cbranch_execz .LBB0_1372
	s_bcnt1_i32_b64 s0, s[10:11]
	v_mov_b32_e32 v0, s0
	global_atomic_add v185, v0, s[6:7]
